# accumulator zeroing by 64-bit moves; redundant zero-init before fp8 cvt pairs dropped
# speedup vs baseline: 1.0030x; 1.0025x over previous
.LBB0_309:
	s_ashr_i32 s71, s70, 31
	s_lshl_b64 s[0:1], s[70:71], 19
	s_add_u32 s72, s47, s0
	s_addc_u32 s73, s49, s1
	s_and_b64 s[0:1], s[74:75], exec
	s_cselect_b32 s0, s73, s9
	s_cselect_b32 s1, s72, s8
	s_ashr_i32 s69, s68, 31
	s_lshl_b64 s[2:3], s[68:69], 19
	s_add_u32 s76, s51, s2
	s_addc_u32 s77, s53, s3
	s_and_b64 s[2:3], s[74:75], exec
	s_cselect_b32 s3, s77, s11
	s_cselect_b32 s7, s76, s10
	s_add_u32 s8, s8, 0x40080
	s_addc_u32 s9, s9, 0
	s_add_u32 s14, s10, 0x100
	v_mov_b32_e32 v34, 0
	s_addc_u32 s15, s11, 0
	s_mov_b32 s16, -2
	v_mov_b64_e32 v[34:35], 0
	v_mov_b64_e32 v[36:37], 0
	v_mov_b64_e32 v[38:39], 0
	v_mov_b64_e32 v[40:41], 0
	v_mov_b64_e32 v[42:43], 0
	v_mov_b64_e32 v[44:45], 0
	v_mov_b64_e32 v[46:47], 0
	v_mov_b64_e32 v[48:49], 0
	v_mov_b64_e32 v[50:51], 0
	v_mov_b64_e32 v[52:53], 0
	v_mov_b64_e32 v[54:55], 0
	v_mov_b64_e32 v[56:57], 0
	v_mov_b64_e32 v[58:59], 0
	v_mov_b64_e32 v[60:61], 0
	v_mov_b64_e32 v[62:63], 0
	v_mov_b64_e32 v[64:65], 0
	v_mov_b64_e32 v[66:67], 0
	v_mov_b64_e32 v[68:69], 0
	v_mov_b64_e32 v[70:71], 0
	v_mov_b64_e32 v[72:73], 0
	v_mov_b64_e32 v[74:75], 0
	v_mov_b64_e32 v[76:77], 0
	v_mov_b64_e32 v[78:79], 0
	v_mov_b64_e32 v[80:81], 0
	v_mov_b64_e32 v[82:83], 0
	v_mov_b64_e32 v[84:85], 0
	v_mov_b64_e32 v[86:87], 0
	v_mov_b64_e32 v[88:89], 0
	v_mov_b64_e32 v[90:91], 0
	v_mov_b64_e32 v[92:93], 0
	v_mov_b64_e32 v[94:95], 0
	v_mov_b64_e32 v[96:97], 0
	v_mov_b64_e32 v[98:99], 0
	v_mov_b64_e32 v[100:101], 0
	v_mov_b64_e32 v[102:103], 0
	v_mov_b64_e32 v[104:105], 0
	v_mov_b64_e32 v[106:107], 0
	v_mov_b64_e32 v[108:109], 0
	v_mov_b64_e32 v[110:111], 0
	v_mov_b64_e32 v[112:113], 0
	v_mov_b64_e32 v[114:115], 0
	v_mov_b64_e32 v[116:117], 0
	v_mov_b64_e32 v[118:119], 0
	v_mov_b64_e32 v[120:121], 0
	v_mov_b64_e32 v[122:123], 0
	v_mov_b64_e32 v[124:125], 0
	v_mov_b64_e32 v[126:127], 0
	v_mov_b64_e32 v[128:129], 0
	v_mov_b64_e32 v[130:131], 0
	v_mov_b64_e32 v[132:133], 0
	v_mov_b64_e32 v[134:135], 0
	v_mov_b64_e32 v[136:137], 0
	v_mov_b64_e32 v[138:139], 0
	v_mov_b64_e32 v[140:141], 0
	v_mov_b64_e32 v[142:143], 0
	v_mov_b64_e32 v[144:145], 0
	v_mov_b64_e32 v[146:147], 0
	v_mov_b64_e32 v[148:149], 0
	v_mov_b64_e32 v[150:151], 0
	v_mov_b64_e32 v[152:153], 0
	v_mov_b64_e32 v[154:155], 0
	v_mov_b64_e32 v[156:157], 0
	v_mov_b64_e32 v[158:159], 0
	v_mov_b64_e32 v[160:161], 0

.LBB0_458:
	s_ashr_i32 s53, s52, 31
	s_lshl_b64 s[42:43], s[52:53], 19
	s_add_u32 s54, s47, s42
	s_addc_u32 s55, s49, s43
	s_and_b64 s[42:43], s[4:5], exec
	s_cselect_b32 s35, s55, s63
	s_cselect_b32 s42, s54, s62
	s_ashr_i32 s51, s50, 31
	s_lshl_b64 s[56:57], s[50:51], 19
	s_add_u32 s56, s0, s56
	s_addc_u32 s57, s1, s57
	s_and_b64 s[66:67], s[4:5], exec
	s_cselect_b32 s43, s57, s65
	s_cselect_b32 s51, s56, s64
	s_add_u32 s62, s62, 0x40080
	s_addc_u32 s63, s63, 0
	s_add_u32 s53, s64, 0x100
	v_mov_b32_e32 v34, 0
	s_addc_u32 s59, s65, 0
	s_mov_b32 s74, -2
	v_mov_b64_e32 v[34:35], 0
	v_mov_b64_e32 v[36:37], 0
	v_mov_b64_e32 v[38:39], 0
	v_mov_b64_e32 v[40:41], 0
	v_mov_b64_e32 v[42:43], 0
	v_mov_b64_e32 v[44:45], 0
	v_mov_b64_e32 v[46:47], 0
	v_mov_b64_e32 v[48:49], 0
	v_mov_b64_e32 v[50:51], 0
	v_mov_b64_e32 v[52:53], 0
	v_mov_b64_e32 v[54:55], 0
	v_mov_b64_e32 v[56:57], 0
	v_mov_b64_e32 v[58:59], 0
	v_mov_b64_e32 v[60:61], 0
	v_mov_b64_e32 v[62:63], 0
	v_mov_b64_e32 v[64:65], 0
	v_mov_b64_e32 v[66:67], 0
	v_mov_b64_e32 v[68:69], 0
	v_mov_b64_e32 v[70:71], 0
	v_mov_b64_e32 v[72:73], 0
	v_mov_b64_e32 v[74:75], 0
	v_mov_b64_e32 v[76:77], 0
	v_mov_b64_e32 v[78:79], 0
	v_mov_b64_e32 v[80:81], 0
	v_mov_b64_e32 v[82:83], 0
	v_mov_b64_e32 v[84:85], 0
	v_mov_b64_e32 v[86:87], 0
	v_mov_b64_e32 v[88:89], 0
	v_mov_b64_e32 v[90:91], 0
	v_mov_b64_e32 v[92:93], 0
	v_mov_b64_e32 v[94:95], 0
	v_mov_b64_e32 v[96:97], 0
	v_mov_b64_e32 v[98:99], 0
	v_mov_b64_e32 v[100:101], 0
	v_mov_b64_e32 v[102:103], 0
	v_mov_b64_e32 v[104:105], 0
	v_mov_b64_e32 v[106:107], 0
	v_mov_b64_e32 v[108:109], 0
	v_mov_b64_e32 v[110:111], 0
	v_mov_b64_e32 v[112:113], 0
	v_mov_b64_e32 v[114:115], 0
	v_mov_b64_e32 v[116:117], 0
	v_mov_b64_e32 v[118:119], 0
	v_mov_b64_e32 v[120:121], 0
	v_mov_b64_e32 v[122:123], 0
	v_mov_b64_e32 v[124:125], 0
	v_mov_b64_e32 v[126:127], 0
	v_mov_b64_e32 v[128:129], 0
	v_mov_b64_e32 v[130:131], 0
	v_mov_b64_e32 v[132:133], 0
	v_mov_b64_e32 v[134:135], 0
	v_mov_b64_e32 v[136:137], 0
	v_mov_b64_e32 v[138:139], 0
	v_mov_b64_e32 v[140:141], 0
	v_mov_b64_e32 v[142:143], 0
	v_mov_b64_e32 v[144:145], 0
	v_mov_b64_e32 v[146:147], 0
	v_mov_b64_e32 v[148:149], 0
	v_mov_b64_e32 v[150:151], 0
	v_mov_b64_e32 v[152:153], 0
	v_mov_b64_e32 v[154:155], 0
	v_mov_b64_e32 v[156:157], 0
	v_mov_b64_e32 v[158:159], 0
	v_mov_b64_e32 v[160:161], 0

.LBB0_881:
	s_ashr_i32 s49, s48, 31
	s_lshl_b64 s[42:43], s[48:49], 19
	s_add_u32 s50, s1, s42
	s_addc_u32 s51, s3, s43
	s_and_b64 s[42:43], s[4:5], exec
	s_cselect_b32 s35, s51, s57
	s_cselect_b32 s42, s50, s56
	s_ashr_i32 s45, s44, 31
	s_lshl_b64 s[52:53], s[44:45], 19
	s_add_u32 s52, s14, s52
	s_addc_u32 s53, s15, s53
	s_and_b64 s[60:61], s[4:5], exec
	s_cselect_b32 s43, s53, s59
	s_cselect_b32 s45, s52, s58
	s_add_u32 s56, s56, 0x40080
	s_addc_u32 s57, s57, 0
	s_add_u32 s49, s58, 0x100
	v_mov_b32_e32 v34, 0
	s_addc_u32 s65, s59, 0
	s_mov_b32 s66, -2
	v_mov_b64_e32 v[34:35], 0
	v_mov_b64_e32 v[36:37], 0
	v_mov_b64_e32 v[38:39], 0
	v_mov_b64_e32 v[40:41], 0
	v_mov_b64_e32 v[42:43], 0
	v_mov_b64_e32 v[44:45], 0
	v_mov_b64_e32 v[46:47], 0
	v_mov_b64_e32 v[48:49], 0
	v_mov_b64_e32 v[50:51], 0
	v_mov_b64_e32 v[52:53], 0
	v_mov_b64_e32 v[54:55], 0
	v_mov_b64_e32 v[56:57], 0
	v_mov_b64_e32 v[58:59], 0
	v_mov_b64_e32 v[60:61], 0
	v_mov_b64_e32 v[62:63], 0
	v_mov_b64_e32 v[64:65], 0
	v_mov_b64_e32 v[66:67], 0
	v_mov_b64_e32 v[68:69], 0
	v_mov_b64_e32 v[70:71], 0
	v_mov_b64_e32 v[72:73], 0
	v_mov_b64_e32 v[74:75], 0
	v_mov_b64_e32 v[76:77], 0
	v_mov_b64_e32 v[78:79], 0
	v_mov_b64_e32 v[80:81], 0
	v_mov_b64_e32 v[82:83], 0
	v_mov_b64_e32 v[84:85], 0
	v_mov_b64_e32 v[86:87], 0
	v_mov_b64_e32 v[88:89], 0
	v_mov_b64_e32 v[90:91], 0
	v_mov_b64_e32 v[92:93], 0
	v_mov_b64_e32 v[94:95], 0
	v_mov_b64_e32 v[96:97], 0
	v_mov_b64_e32 v[98:99], 0
	v_mov_b64_e32 v[100:101], 0
	v_mov_b64_e32 v[102:103], 0
	v_mov_b64_e32 v[104:105], 0
	v_mov_b64_e32 v[106:107], 0
	v_mov_b64_e32 v[108:109], 0
	v_mov_b64_e32 v[110:111], 0
	v_mov_b64_e32 v[112:113], 0
	v_mov_b64_e32 v[114:115], 0
	v_mov_b64_e32 v[116:117], 0
	v_mov_b64_e32 v[118:119], 0
	v_mov_b64_e32 v[120:121], 0
	v_mov_b64_e32 v[122:123], 0
	v_mov_b64_e32 v[124:125], 0
	v_mov_b64_e32 v[126:127], 0
	v_mov_b64_e32 v[128:129], 0
	v_mov_b64_e32 v[130:131], 0
	v_mov_b64_e32 v[132:133], 0
	v_mov_b64_e32 v[134:135], 0
	v_mov_b64_e32 v[136:137], 0
	v_mov_b64_e32 v[138:139], 0
	v_mov_b64_e32 v[140:141], 0
	v_mov_b64_e32 v[142:143], 0
	v_mov_b64_e32 v[144:145], 0
	v_mov_b64_e32 v[146:147], 0
	v_mov_b64_e32 v[148:149], 0
	v_mov_b64_e32 v[150:151], 0
	v_mov_b64_e32 v[152:153], 0
	v_mov_b64_e32 v[154:155], 0
	v_mov_b64_e32 v[156:157], 0
	v_mov_b64_e32 v[158:159], 0
	v_mov_b64_e32 v[160:161], 0

.LBB0_1000:
	s_ashr_i32 s51, s50, 31
	s_lshl_b64 s[42:43], s[50:51], 19
	s_add_u32 s44, s14, s42
	s_addc_u32 s45, s15, s43
	s_and_b64 s[42:43], s[4:5], exec
	s_cselect_b32 s35, s45, s57
	s_cselect_b32 s42, s44, s56
	s_ashr_i32 s49, s48, 31
	s_lshl_b64 s[52:53], s[48:49], 19
	s_add_u32 s52, s25, s52
	s_addc_u32 s53, s33, s53
	s_and_b64 s[60:61], s[4:5], exec
	s_cselect_b32 s43, s53, s59
	s_cselect_b32 s49, s52, s58
	s_add_u32 s56, s56, 0x40080
	s_addc_u32 s57, s57, 0
	s_add_u32 s51, s58, 0x100
	v_mov_b32_e32 v34, 0
	s_addc_u32 s65, s59, 0
	s_mov_b32 s66, -2
	v_mov_b64_e32 v[34:35], 0
	v_mov_b64_e32 v[36:37], 0
	v_mov_b64_e32 v[38:39], 0
	v_mov_b64_e32 v[40:41], 0
	v_mov_b64_e32 v[42:43], 0
	v_mov_b64_e32 v[44:45], 0
	v_mov_b64_e32 v[46:47], 0
	v_mov_b64_e32 v[48:49], 0
	v_mov_b64_e32 v[50:51], 0
	v_mov_b64_e32 v[52:53], 0
	v_mov_b64_e32 v[54:55], 0
	v_mov_b64_e32 v[56:57], 0
	v_mov_b64_e32 v[58:59], 0
	v_mov_b64_e32 v[60:61], 0
	v_mov_b64_e32 v[62:63], 0
	v_mov_b64_e32 v[64:65], 0
	v_mov_b64_e32 v[66:67], 0
	v_mov_b64_e32 v[68:69], 0
	v_mov_b64_e32 v[70:71], 0
	v_mov_b64_e32 v[72:73], 0
	v_mov_b64_e32 v[74:75], 0
	v_mov_b64_e32 v[76:77], 0
	v_mov_b64_e32 v[78:79], 0
	v_mov_b64_e32 v[80:81], 0
	v_mov_b64_e32 v[82:83], 0
	v_mov_b64_e32 v[84:85], 0
	v_mov_b64_e32 v[86:87], 0
	v_mov_b64_e32 v[88:89], 0
	v_mov_b64_e32 v[90:91], 0
	v_mov_b64_e32 v[92:93], 0
	v_mov_b64_e32 v[94:95], 0
	v_mov_b64_e32 v[96:97], 0
	v_mov_b64_e32 v[98:99], 0
	v_mov_b64_e32 v[100:101], 0
	v_mov_b64_e32 v[102:103], 0
	v_mov_b64_e32 v[104:105], 0
	v_mov_b64_e32 v[106:107], 0
	v_mov_b64_e32 v[108:109], 0
	v_mov_b64_e32 v[110:111], 0
	v_mov_b64_e32 v[112:113], 0
	v_mov_b64_e32 v[114:115], 0
	v_mov_b64_e32 v[116:117], 0
	v_mov_b64_e32 v[118:119], 0
	v_mov_b64_e32 v[120:121], 0
	v_mov_b64_e32 v[122:123], 0
	v_mov_b64_e32 v[124:125], 0
	v_mov_b64_e32 v[126:127], 0
	v_mov_b64_e32 v[128:129], 0
	v_mov_b64_e32 v[130:131], 0
	v_mov_b64_e32 v[132:133], 0
	v_mov_b64_e32 v[134:135], 0
	v_mov_b64_e32 v[136:137], 0
	v_mov_b64_e32 v[138:139], 0
	v_mov_b64_e32 v[140:141], 0
	v_mov_b64_e32 v[142:143], 0
	v_mov_b64_e32 v[144:145], 0
	v_mov_b64_e32 v[146:147], 0
	v_mov_b64_e32 v[148:149], 0
	v_mov_b64_e32 v[150:151], 0
	v_mov_b64_e32 v[152:153], 0
	v_mov_b64_e32 v[154:155], 0
	v_mov_b64_e32 v[156:157], 0
	v_mov_b64_e32 v[158:159], 0
	v_mov_b64_e32 v[160:161], 0

.LBB0_1079:
	s_ashr_i32 s49, s48, 31
	s_lshl_b64 s[42:43], s[48:49], 19
	s_add_u32 s50, s1, s42
	s_addc_u32 s51, s3, s43
	s_and_b64 s[42:43], s[4:5], exec
	s_cselect_b32 s35, s51, s57
	s_cselect_b32 s42, s50, s56
	s_ashr_i32 s45, s44, 31
	s_lshl_b64 s[52:53], s[44:45], 19
	s_add_u32 s52, s14, s52
	s_addc_u32 s53, s15, s53
	s_and_b64 s[60:61], s[4:5], exec
	s_cselect_b32 s43, s53, s59
	s_cselect_b32 s45, s52, s58
	s_add_u32 s56, s56, 0x40080
	s_addc_u32 s57, s57, 0
	s_add_u32 s49, s58, 0x100
	v_mov_b32_e32 v34, 0
	s_addc_u32 s66, s59, 0
	s_mov_b32 s67, -2
	v_mov_b64_e32 v[34:35], 0
	v_mov_b64_e32 v[36:37], 0
	v_mov_b64_e32 v[38:39], 0
	v_mov_b64_e32 v[40:41], 0
	v_mov_b64_e32 v[42:43], 0
	v_mov_b64_e32 v[44:45], 0
	v_mov_b64_e32 v[46:47], 0
	v_mov_b64_e32 v[48:49], 0
	v_mov_b64_e32 v[50:51], 0
	v_mov_b64_e32 v[52:53], 0
	v_mov_b64_e32 v[54:55], 0
	v_mov_b64_e32 v[56:57], 0
	v_mov_b64_e32 v[58:59], 0
	v_mov_b64_e32 v[60:61], 0
	v_mov_b64_e32 v[62:63], 0
	v_mov_b64_e32 v[64:65], 0
	v_mov_b64_e32 v[66:67], 0
	v_mov_b64_e32 v[68:69], 0
	v_mov_b64_e32 v[70:71], 0
	v_mov_b64_e32 v[72:73], 0
	v_mov_b64_e32 v[74:75], 0
	v_mov_b64_e32 v[76:77], 0
	v_mov_b64_e32 v[78:79], 0
	v_mov_b64_e32 v[80:81], 0
	v_mov_b64_e32 v[82:83], 0
	v_mov_b64_e32 v[84:85], 0
	v_mov_b64_e32 v[86:87], 0
	v_mov_b64_e32 v[88:89], 0
	v_mov_b64_e32 v[90:91], 0
	v_mov_b64_e32 v[92:93], 0
	v_mov_b64_e32 v[94:95], 0
	v_mov_b64_e32 v[96:97], 0
	v_mov_b64_e32 v[98:99], 0
	v_mov_b64_e32 v[100:101], 0
	v_mov_b64_e32 v[102:103], 0
	v_mov_b64_e32 v[104:105], 0
	v_mov_b64_e32 v[106:107], 0
	v_mov_b64_e32 v[108:109], 0
	v_mov_b64_e32 v[110:111], 0
	v_mov_b64_e32 v[112:113], 0
	v_mov_b64_e32 v[114:115], 0
	v_mov_b64_e32 v[116:117], 0
	v_mov_b64_e32 v[118:119], 0
	v_mov_b64_e32 v[120:121], 0
	v_mov_b64_e32 v[122:123], 0
	v_mov_b64_e32 v[124:125], 0
	v_mov_b64_e32 v[126:127], 0
	v_mov_b64_e32 v[128:129], 0
	v_mov_b64_e32 v[130:131], 0
	v_mov_b64_e32 v[132:133], 0
	v_mov_b64_e32 v[134:135], 0
	v_mov_b64_e32 v[136:137], 0
	v_mov_b64_e32 v[138:139], 0
	v_mov_b64_e32 v[140:141], 0
	v_mov_b64_e32 v[142:143], 0
	v_mov_b64_e32 v[144:145], 0
	v_mov_b64_e32 v[146:147], 0
	v_mov_b64_e32 v[148:149], 0
	v_mov_b64_e32 v[150:151], 0
	v_mov_b64_e32 v[152:153], 0
	v_mov_b64_e32 v[154:155], 0
	v_mov_b64_e32 v[156:157], 0
	v_mov_b64_e32 v[158:159], 0
	v_mov_b64_e32 v[160:161], 0

.LBB0_1574:
	s_ashr_i32 s47, s46, 31
	s_lshl_b64 s[42:43], s[46:47], 19
	s_add_u32 s48, s14, s42
	s_addc_u32 s49, s15, s43
	s_and_b64 s[42:43], s[6:7], exec
	s_cselect_b32 s1, s49, s53
	s_cselect_b32 s47, s48, s52
	s_ashr_i32 s45, s44, 31
	s_lshl_b64 s[42:43], s[44:45], 14
	s_waitcnt lgkmcnt(0)
	s_add_u32 s35, s16, s42
	s_addc_u32 s50, s17, s43
	s_lshl_b32 s44, s2, 7
	s_ashr_i32 s45, s44, 31
	s_lshl_b64 s[42:43], s[44:45], 2
	s_add_u32 s2, s35, s42
	s_addc_u32 s35, s50, s43
	s_add_u32 s50, s2, s68
	s_addc_u32 s51, s35, 0
	s_add_u32 s45, s52, 0x100
	v_mov_b32_e32 v82, 0
	v_mov_b32_e32 v230, v218
	v_mov_b32_e32 v231, v217
	v_mov_b32_e32 v232, v220
	v_mov_b32_e32 v233, v217
	s_addc_u32 s76, s53, 0
	s_mov_b32 s77, -2
	s_mov_b64 s[52:53], s[24:25]
	v_mov_b32_e32 v250, v252
	v_mov_b32_e32 v251, v228
	v_mov_b64_e32 v[82:83], 0
	v_mov_b64_e32 v[84:85], 0
	v_mov_b64_e32 v[86:87], 0
	v_mov_b64_e32 v[88:89], 0
	v_mov_b64_e32 v[90:91], 0
	v_mov_b64_e32 v[92:93], 0
	v_mov_b64_e32 v[94:95], 0
	v_mov_b64_e32 v[96:97], 0
	v_mov_b64_e32 v[98:99], 0
	v_mov_b64_e32 v[100:101], 0
	v_mov_b64_e32 v[102:103], 0
	v_mov_b64_e32 v[104:105], 0
	v_mov_b64_e32 v[106:107], 0
	v_mov_b64_e32 v[108:109], 0
	v_mov_b64_e32 v[110:111], 0
	v_mov_b64_e32 v[112:113], 0
	v_mov_b64_e32 v[114:115], 0
	v_mov_b64_e32 v[116:117], 0
	v_mov_b64_e32 v[118:119], 0
	v_mov_b64_e32 v[120:121], 0
	v_mov_b64_e32 v[122:123], 0
	v_mov_b64_e32 v[124:125], 0
	v_mov_b64_e32 v[126:127], 0
	v_mov_b64_e32 v[128:129], 0
	v_mov_b64_e32 v[130:131], 0
	v_mov_b64_e32 v[132:133], 0
	v_mov_b64_e32 v[134:135], 0
	v_mov_b64_e32 v[136:137], 0
	v_mov_b64_e32 v[138:139], 0
	v_mov_b64_e32 v[140:141], 0
	v_mov_b64_e32 v[142:143], 0
	v_mov_b64_e32 v[144:145], 0
	v_mov_b64_e32 v[146:147], 0
	v_mov_b64_e32 v[148:149], 0
	v_mov_b64_e32 v[150:151], 0
	v_mov_b64_e32 v[152:153], 0
	v_mov_b64_e32 v[154:155], 0
	v_mov_b64_e32 v[156:157], 0
	v_mov_b64_e32 v[158:159], 0
	v_mov_b64_e32 v[160:161], 0
	v_mov_b64_e32 v[162:163], 0
	v_mov_b64_e32 v[164:165], 0
	v_mov_b64_e32 v[166:167], 0
	v_mov_b64_e32 v[168:169], 0
	v_mov_b64_e32 v[170:171], 0
	v_mov_b64_e32 v[172:173], 0
	v_mov_b64_e32 v[174:175], 0
	v_mov_b64_e32 v[176:177], 0
	v_mov_b64_e32 v[178:179], 0
	v_mov_b64_e32 v[180:181], 0
	v_mov_b64_e32 v[182:183], 0
	v_mov_b64_e32 v[184:185], 0
	v_mov_b64_e32 v[186:187], 0
	v_mov_b64_e32 v[188:189], 0
	v_mov_b64_e32 v[190:191], 0
	v_mov_b64_e32 v[192:193], 0
	v_mov_b64_e32 v[194:195], 0
	v_mov_b64_e32 v[196:197], 0
	v_mov_b64_e32 v[198:199], 0
	v_mov_b64_e32 v[200:201], 0
	v_mov_b64_e32 v[202:203], 0
	v_mov_b64_e32 v[204:205], 0
	v_mov_b64_e32 v[206:207], 0
	v_mov_b64_e32 v[208:209], 0
	s_branch .LBB0_1576

.LBB0_1590:
	v_fmamk_f32 v3, v206, 0x3d000000, v66
	v_min_f32_e32 v3, 0x40e00000, v3
	v_mul_f32_e32 v4, 0xc01d265f, v3
	v_exp_f32_e32 v7, v4
	v_fmamk_f32 v8, v207, 0x3d000000, v67
	v_min_f32_e32 v8, 0x40e00000, v8
	v_mul_f32_e32 v9, 0xc01d265f, v8
	v_add_f32_e32 v7, 1.0, v7
	v_rcp_f32_e32 v7, v7
	v_exp_f32_e32 v9, v9
	v_fmamk_f32 v10, v209, 0x3d000000, v69
	v_min_f32_e32 v10, 0x40e00000, v10
	v_mul_f32_e32 v3, v3, v7
	v_add_f32_e32 v7, 1.0, v9
	v_rcp_f32_e32 v7, v7
	v_mul_f32_e32 v11, 0xc01d265f, v10
	v_exp_f32_e32 v11, v11
	v_mul_f32_e32 v7, v8, v7
	v_fmamk_f32 v8, v208, 0x3d000000, v68
	v_min_f32_e32 v8, 0x40e00000, v8
	v_mul_f32_e32 v9, 0xc01d265f, v8
	v_exp_f32_e32 v9, v9
	s_lshl_b32 s0, s0, 8
	v_mbcnt_lo_u32_b32 v2, -1, 0
	v_mbcnt_hi_u32_b32 v2, -1, v2
	s_add_i32 s0, s0, s63
	v_add_f32_e32 v9, 1.0, v9
	v_rcp_f32_e32 v9, v9
	v_and_or_b32 v6, v2, 15, s0
	v_ashrrev_i32_e32 v2, 1, v2
	s_or_b32 s0, s44, s64
	v_and_b32_e32 v2, -8, v2
	v_mul_f32_e32 v8, v8, v9
	v_add_f32_e32 v9, 1.0, v11
	v_add_u32_e32 v4, s0, v2
	v_fmamk_f32 v2, v202, 0x3d000000, v74
	v_rcp_f32_e32 v9, v9
	v_med3_f32 v2, v2, s69, v247
	v_fma_f32 v2, v3, v2, v3
	v_fmamk_f32 v3, v203, 0x3d000000, v75
	v_med3_f32 v3, v3, s69, v247
	v_mul_f32_e32 v9, v10, v9
	v_fmamk_f32 v10, v198, 0x3d000000, v70
	v_min_f32_e32 v10, 0x40e00000, v10
	v_fma_f32 v3, v7, v3, v7
	v_fmamk_f32 v7, v204, 0x3d000000, v76
	v_mul_f32_e32 v11, 0xc01d265f, v10
	v_med3_f32 v7, v7, s69, v247
	v_exp_f32_e32 v11, v11
	v_fma_f32 v7, v8, v7, v8
	v_fmamk_f32 v8, v205, 0x3d000000, v77
	v_med3_f32 v8, v8, s69, v247
	v_fma_f32 v12, v9, v8, v9
	v_add_f32_e32 v9, 1.0, v11
	v_fmamk_f32 v11, v199, 0x3d000000, v71
	v_min_f32_e32 v11, 0x40e00000, v11
	v_mul_f32_e32 v13, 0xc01d265f, v11
	v_rcp_f32_e32 v9, v9
	v_exp_f32_e32 v13, v13
	v_fmamk_f32 v8, v194, 0x3d000000, v78
	v_med3_f32 v8, v8, s69, v247
	v_mul_f32_e32 v9, v10, v9
	v_add_f32_e32 v10, 1.0, v13
	v_rcp_f32_e32 v10, v10
	v_fma_f32 v13, v9, v8, v9
	v_fmamk_f32 v8, v195, 0x3d000000, v79
	v_mul_f32_e32 v9, v11, v10
	v_fmamk_f32 v10, v200, 0x3d000000, v72
	v_min_f32_e32 v10, 0x40e00000, v10
	v_mul_f32_e32 v11, 0xc01d265f, v10
	v_exp_f32_e32 v11, v11
	v_med3_f32 v8, v8, s69, v247
	v_fma_f32 v14, v9, v8, v9
	v_add_f32_e32 v9, 1.0, v11
	v_fmamk_f32 v11, v201, 0x3d000000, v73
	v_min_f32_e32 v11, 0x40e00000, v11
	v_mul_f32_e32 v15, 0xc01d265f, v11
	v_rcp_f32_e32 v9, v9
	v_exp_f32_e32 v15, v15
	v_fmamk_f32 v8, v196, 0x3d000000, v80
	v_med3_f32 v8, v8, s69, v247
	v_mul_f32_e32 v9, v10, v9
	v_add_f32_e32 v10, 1.0, v15
	v_fma_f32 v15, v9, v8, v9
	v_fmamk_f32 v8, v197, 0x3d000000, v81
	v_rcp_f32_e32 v10, v10
	v_med3_f32 v16, v8, s69, v247
	v_cvt_pk_fp8_f32 v8, v2, v3
	v_cvt_pk_fp8_f32 v9, v13, v14
	v_mul_f32_e32 v10, v11, v10
	v_fma_f32 v2, v10, v16, v10
	v_cvt_pk_fp8_f32 v8, v7, v12 op_sel:[0,0,1]
	v_ashrrev_i32_e32 v7, 31, v6
	v_cvt_pk_fp8_f32 v9, v15, v2 op_sel:[0,0,1]
	v_lshlrev_b64 v[2:3], 11, v[6:7]
	v_fmamk_f32 v7, v190, 0x3d000000, v66
	v_min_f32_e32 v7, 0x40e00000, v7
	v_mul_f32_e32 v10, 0xc01d265f, v7
	v_exp_f32_e32 v10, v10
	v_ashrrev_i32_e32 v5, 31, v4
	v_lshl_add_u64 v[2:3], s[20:21], 0, v[2:3]
	v_lshl_add_u64 v[2:3], v[2:3], 0, v[4:5]
	global_store_dwordx2 v[2:3], v[8:9], off
	v_add_f32_e32 v9, 1.0, v10
	v_fmamk_f32 v10, v191, 0x3d000000, v67
	v_min_f32_e32 v10, 0x40e00000, v10
	v_mul_f32_e32 v11, 0xc01d265f, v10
	v_rcp_f32_e32 v9, v9
	v_exp_f32_e32 v11, v11
	v_fmamk_f32 v12, v193, 0x3d000000, v69
	v_min_f32_e32 v12, 0x40e00000, v12
	v_mul_f32_e32 v7, v7, v9
	v_add_f32_e32 v9, 1.0, v11
	v_rcp_f32_e32 v9, v9
	v_mul_f32_e32 v13, 0xc01d265f, v12
	v_exp_f32_e32 v13, v13
	v_mul_f32_e32 v9, v10, v9
	v_fmamk_f32 v10, v192, 0x3d000000, v68
	v_min_f32_e32 v10, 0x40e00000, v10
	v_mul_f32_e32 v11, 0xc01d265f, v10
	v_exp_f32_e32 v11, v11
	v_fmamk_f32 v14, v183, 0x3d000000, v71
	v_min_f32_e32 v14, 0x40e00000, v14
	v_mul_f32_e32 v15, 0xc01d265f, v14
	v_add_f32_e32 v11, 1.0, v11
	v_rcp_f32_e32 v11, v11
	v_exp_f32_e32 v15, v15
	v_fmamk_f32 v8, v186, 0x3d000000, v74
	v_mul_f32_e32 v10, v10, v11
	v_add_f32_e32 v11, 1.0, v13
	v_rcp_f32_e32 v11, v11
	v_med3_f32 v8, v8, s69, v247
	v_fma_f32 v7, v7, v8, v7
	v_mul_f32_e32 v11, v12, v11
	v_fmamk_f32 v12, v182, 0x3d000000, v70
	v_min_f32_e32 v12, 0x40e00000, v12
	v_mul_f32_e32 v13, 0xc01d265f, v12
	v_exp_f32_e32 v13, v13
	v_fmamk_f32 v8, v187, 0x3d000000, v75
	v_med3_f32 v8, v8, s69, v247
	v_add_f32_e32 v13, 1.0, v13
	v_rcp_f32_e32 v13, v13
	v_fma_f32 v9, v9, v8, v9
	v_fmamk_f32 v8, v188, 0x3d000000, v76
	v_med3_f32 v8, v8, s69, v247
	v_mul_f32_e32 v12, v12, v13
	v_add_f32_e32 v13, 1.0, v15
	v_rcp_f32_e32 v13, v13
	v_fma_f32 v10, v10, v8, v10
	v_fmamk_f32 v8, v189, 0x3d000000, v77
	v_mul_f32_e32 v13, v14, v13
	v_fmamk_f32 v14, v184, 0x3d000000, v72
	v_min_f32_e32 v14, 0x40e00000, v14
	v_mul_f32_e32 v15, 0xc01d265f, v14
	v_med3_f32 v8, v8, s69, v247
	v_exp_f32_e32 v15, v15
	v_fma_f32 v11, v11, v8, v11
	v_fmamk_f32 v8, v178, 0x3d000000, v78
	v_med3_f32 v8, v8, s69, v247
	v_fmamk_f32 v16, v185, 0x3d000000, v73
	v_min_f32_e32 v16, 0x40e00000, v16
	v_fma_f32 v12, v12, v8, v12
	v_fmamk_f32 v8, v179, 0x3d000000, v79
	v_add_f32_e32 v15, 1.0, v15
	v_mul_f32_e32 v17, 0xc01d265f, v16
	v_med3_f32 v8, v8, s69, v247
	v_rcp_f32_e32 v15, v15
	v_exp_f32_e32 v17, v17
	v_fma_f32 v13, v13, v8, v13
	v_fmamk_f32 v8, v180, 0x3d000000, v80
	v_med3_f32 v8, v8, s69, v247
	v_mul_f32_e32 v14, v14, v15
	v_add_f32_e32 v15, 1.0, v17
	v_fma_f32 v14, v14, v8, v14
	v_fmamk_f32 v8, v181, 0x3d000000, v81
	v_rcp_f32_e32 v15, v15
	v_med3_f32 v17, v8, s69, v247
	v_cvt_pk_fp8_f32 v8, v7, v9
	v_cvt_pk_fp8_f32 v9, v12, v13
	v_mul_f32_e32 v15, v16, v15
	v_fma_f32 v7, v15, v17, v15
	v_cvt_pk_fp8_f32 v8, v10, v11 op_sel:[0,0,1]
	v_cvt_pk_fp8_f32 v9, v14, v7 op_sel:[0,0,1]
	v_or_b32_e32 v10, 16, v6
	v_fmamk_f32 v7, v174, 0x3d000000, v66
	v_ashrrev_i32_e32 v11, 31, v10
	v_min_f32_e32 v7, 0x40e00000, v7
	v_lshlrev_b64 v[10:11], 11, v[10:11]
	v_mul_f32_e32 v12, 0xc01d265f, v7
	v_lshl_add_u64 v[10:11], s[20:21], 0, v[10:11]
	v_exp_f32_e32 v12, v12
	v_lshl_add_u64 v[10:11], v[10:11], 0, v[4:5]
	global_store_dwordx2 v[10:11], v[8:9], off
	v_fmamk_f32 v10, v175, 0x3d000000, v67
	v_min_f32_e32 v10, 0x40e00000, v10
	v_mul_f32_e32 v11, 0xc01d265f, v10
	v_add_f32_e32 v9, 1.0, v12
	v_rcp_f32_e32 v9, v9
	v_exp_f32_e32 v11, v11
	v_fmamk_f32 v12, v177, 0x3d000000, v69
	v_min_f32_e32 v12, 0x40e00000, v12
	v_mul_f32_e32 v7, v7, v9
	v_add_f32_e32 v9, 1.0, v11
	v_rcp_f32_e32 v9, v9
	v_mul_f32_e32 v13, 0xc01d265f, v12
	v_exp_f32_e32 v13, v13
	v_mul_f32_e32 v9, v10, v9
	v_fmamk_f32 v10, v176, 0x3d000000, v68
	v_min_f32_e32 v10, 0x40e00000, v10
	v_mul_f32_e32 v11, 0xc01d265f, v10
	v_exp_f32_e32 v11, v11
	v_fmamk_f32 v14, v167, 0x3d000000, v71
	v_min_f32_e32 v14, 0x40e00000, v14
	v_mul_f32_e32 v15, 0xc01d265f, v14
	v_add_f32_e32 v11, 1.0, v11
	v_rcp_f32_e32 v11, v11
	v_exp_f32_e32 v15, v15
	v_fmamk_f32 v8, v170, 0x3d000000, v74
	v_mul_f32_e32 v10, v10, v11
	v_add_f32_e32 v11, 1.0, v13
	v_rcp_f32_e32 v11, v11
	v_med3_f32 v8, v8, s69, v247
	v_fma_f32 v7, v7, v8, v7
	v_mul_f32_e32 v11, v12, v11
	v_fmamk_f32 v12, v166, 0x3d000000, v70
	v_min_f32_e32 v12, 0x40e00000, v12
	v_mul_f32_e32 v13, 0xc01d265f, v12
	v_exp_f32_e32 v13, v13
	v_fmamk_f32 v8, v171, 0x3d000000, v75
	v_med3_f32 v8, v8, s69, v247
	v_add_f32_e32 v13, 1.0, v13
	v_rcp_f32_e32 v13, v13
	v_fma_f32 v9, v9, v8, v9
	v_fmamk_f32 v8, v172, 0x3d000000, v76
	v_med3_f32 v8, v8, s69, v247
	v_mul_f32_e32 v12, v12, v13
	v_add_f32_e32 v13, 1.0, v15
	v_rcp_f32_e32 v13, v13
	v_fma_f32 v10, v10, v8, v10
	v_fmamk_f32 v8, v173, 0x3d000000, v77
	v_mul_f32_e32 v13, v14, v13
	v_fmamk_f32 v14, v168, 0x3d000000, v72
	v_min_f32_e32 v14, 0x40e00000, v14
	v_mul_f32_e32 v15, 0xc01d265f, v14
	v_med3_f32 v8, v8, s69, v247
	v_exp_f32_e32 v15, v15
	v_fma_f32 v11, v11, v8, v11
	v_fmamk_f32 v8, v162, 0x3d000000, v78
	v_med3_f32 v8, v8, s69, v247
	v_fmamk_f32 v16, v169, 0x3d000000, v73
	v_min_f32_e32 v16, 0x40e00000, v16
	v_fma_f32 v12, v12, v8, v12
	v_fmamk_f32 v8, v163, 0x3d000000, v79
	v_add_f32_e32 v15, 1.0, v15
	v_mul_f32_e32 v17, 0xc01d265f, v16
	v_med3_f32 v8, v8, s69, v247
	v_rcp_f32_e32 v15, v15
	v_exp_f32_e32 v17, v17
	v_fma_f32 v13, v13, v8, v13
	v_fmamk_f32 v8, v164, 0x3d000000, v80
	v_med3_f32 v8, v8, s69, v247
	v_mul_f32_e32 v14, v14, v15
	v_add_f32_e32 v15, 1.0, v17
	v_fma_f32 v14, v14, v8, v14
	v_fmamk_f32 v8, v165, 0x3d000000, v81
	v_rcp_f32_e32 v15, v15
	v_med3_f32 v17, v8, s69, v247
	v_cvt_pk_fp8_f32 v8, v7, v9
	v_cvt_pk_fp8_f32 v9, v12, v13
	v_mul_f32_e32 v15, v16, v15
	v_fma_f32 v7, v15, v17, v15
	v_cvt_pk_fp8_f32 v8, v10, v11 op_sel:[0,0,1]
	v_cvt_pk_fp8_f32 v9, v14, v7 op_sel:[0,0,1]
	v_or_b32_e32 v10, 32, v6
	v_fmamk_f32 v7, v158, 0x3d000000, v66
	v_ashrrev_i32_e32 v11, 31, v10
	v_min_f32_e32 v7, 0x40e00000, v7
	v_lshlrev_b64 v[10:11], 11, v[10:11]
	v_mul_f32_e32 v12, 0xc01d265f, v7
	v_lshl_add_u64 v[10:11], s[20:21], 0, v[10:11]
	v_exp_f32_e32 v12, v12
	v_lshl_add_u64 v[10:11], v[10:11], 0, v[4:5]
	global_store_dwordx2 v[10:11], v[8:9], off
	v_fmamk_f32 v10, v159, 0x3d000000, v67
	v_min_f32_e32 v10, 0x40e00000, v10
	v_mul_f32_e32 v11, 0xc01d265f, v10
	v_add_f32_e32 v9, 1.0, v12
	v_rcp_f32_e32 v9, v9
	v_exp_f32_e32 v11, v11
	v_fmamk_f32 v12, v161, 0x3d000000, v69
	v_min_f32_e32 v12, 0x40e00000, v12
	v_mul_f32_e32 v7, v7, v9
	v_add_f32_e32 v9, 1.0, v11
	v_rcp_f32_e32 v9, v9
	v_mul_f32_e32 v13, 0xc01d265f, v12
	v_exp_f32_e32 v13, v13
	v_mul_f32_e32 v9, v10, v9
	v_fmamk_f32 v10, v160, 0x3d000000, v68
	v_min_f32_e32 v10, 0x40e00000, v10
	v_mul_f32_e32 v11, 0xc01d265f, v10
	v_exp_f32_e32 v11, v11
	v_fmamk_f32 v14, v151, 0x3d000000, v71
	v_min_f32_e32 v14, 0x40e00000, v14
	v_mul_f32_e32 v15, 0xc01d265f, v14
	v_add_f32_e32 v11, 1.0, v11
	v_rcp_f32_e32 v11, v11
	v_exp_f32_e32 v15, v15
	v_fmamk_f32 v8, v154, 0x3d000000, v74
	v_mul_f32_e32 v10, v10, v11
	v_add_f32_e32 v11, 1.0, v13
	v_rcp_f32_e32 v11, v11
	v_med3_f32 v8, v8, s69, v247
	v_fma_f32 v7, v7, v8, v7
	v_mul_f32_e32 v11, v12, v11
	v_fmamk_f32 v12, v150, 0x3d000000, v70
	v_min_f32_e32 v12, 0x40e00000, v12
	v_mul_f32_e32 v13, 0xc01d265f, v12
	v_exp_f32_e32 v13, v13
	v_fmamk_f32 v8, v155, 0x3d000000, v75
	v_med3_f32 v8, v8, s69, v247
	v_add_f32_e32 v13, 1.0, v13
	v_rcp_f32_e32 v13, v13
	v_fma_f32 v9, v9, v8, v9
	v_fmamk_f32 v8, v156, 0x3d000000, v76
	v_med3_f32 v8, v8, s69, v247
	v_mul_f32_e32 v12, v12, v13
	v_add_f32_e32 v13, 1.0, v15
	v_rcp_f32_e32 v13, v13
	v_fma_f32 v10, v10, v8, v10
	v_fmamk_f32 v8, v157, 0x3d000000, v77
	v_mul_f32_e32 v13, v14, v13
	v_fmamk_f32 v14, v152, 0x3d000000, v72
	v_min_f32_e32 v14, 0x40e00000, v14
	v_mul_f32_e32 v15, 0xc01d265f, v14
	v_med3_f32 v8, v8, s69, v247
	v_exp_f32_e32 v15, v15
	v_fma_f32 v11, v11, v8, v11
	v_fmamk_f32 v8, v146, 0x3d000000, v78
	v_med3_f32 v8, v8, s69, v247
	v_fmamk_f32 v16, v153, 0x3d000000, v73
	v_min_f32_e32 v16, 0x40e00000, v16
	v_fma_f32 v12, v12, v8, v12
	v_fmamk_f32 v8, v147, 0x3d000000, v79
	v_add_f32_e32 v15, 1.0, v15
	v_mul_f32_e32 v17, 0xc01d265f, v16
	v_med3_f32 v8, v8, s69, v247
	v_rcp_f32_e32 v15, v15
	v_exp_f32_e32 v17, v17
	v_fma_f32 v13, v13, v8, v13
	v_fmamk_f32 v8, v148, 0x3d000000, v80
	v_med3_f32 v8, v8, s69, v247
	v_mul_f32_e32 v14, v14, v15
	v_add_f32_e32 v15, 1.0, v17
	v_fma_f32 v14, v14, v8, v14
	v_fmamk_f32 v8, v149, 0x3d000000, v81
	v_rcp_f32_e32 v15, v15
	v_med3_f32 v17, v8, s69, v247
	v_cvt_pk_fp8_f32 v8, v7, v9
	v_cvt_pk_fp8_f32 v9, v12, v13
	v_mul_f32_e32 v15, v16, v15
	v_fma_f32 v7, v15, v17, v15
	v_or_b32_e32 v6, 48, v6
	v_cvt_pk_fp8_f32 v9, v14, v7 op_sel:[0,0,1]
	v_ashrrev_i32_e32 v7, 31, v6
	v_lshlrev_b64 v[6:7], 11, v[6:7]
	v_lshl_add_u64 v[6:7], s[20:21], 0, v[6:7]
	v_lshl_add_u64 v[4:5], v[6:7], 0, v[4:5]
	v_fmamk_f32 v6, v143, 0x3d000000, v67
	v_min_f32_e32 v6, 0x40e00000, v6
	v_mul_f32_e32 v7, 0xc01d265f, v6
	v_exp_f32_e32 v7, v7
	v_cvt_pk_fp8_f32 v8, v10, v11 op_sel:[0,0,1]
	v_fmamk_f32 v10, v142, 0x3d000000, v66
	v_min_f32_e32 v10, 0x40e00000, v10
	v_add_f32_e32 v7, 1.0, v7
	v_mul_f32_e32 v11, 0xc01d265f, v10
	v_rcp_f32_e32 v7, v7
	v_exp_f32_e32 v11, v11
	global_store_dwordx2 v[4:5], v[8:9], off
	v_mul_f32_e32 v6, v6, v7
	v_fmamk_f32 v7, v144, 0x3d000000, v68
	v_min_f32_e32 v7, 0x40e00000, v7
	v_add_f32_e32 v5, 1.0, v11
	v_mul_f32_e32 v8, 0xc01d265f, v7
	v_rcp_f32_e32 v5, v5
	v_exp_f32_e32 v8, v8
	v_fmamk_f32 v9, v145, 0x3d000000, v69
	v_min_f32_e32 v9, 0x40e00000, v9
	v_mul_f32_e32 v5, v10, v5
	v_mul_f32_e32 v10, 0xc01d265f, v9
	v_add_f32_e32 v8, 1.0, v8
	v_rcp_f32_e32 v8, v8
	v_exp_f32_e32 v10, v10
	v_fmamk_f32 v11, v135, 0x3d000000, v71
	v_min_f32_e32 v11, 0x40e00000, v11
	v_mul_f32_e32 v7, v7, v8
	v_add_f32_e32 v8, 1.0, v10
	v_rcp_f32_e32 v8, v8
	v_mul_f32_e32 v12, 0xc01d265f, v11
	v_exp_f32_e32 v12, v12
	v_mul_f32_e32 v8, v9, v8
	v_fmamk_f32 v9, v134, 0x3d000000, v70
	v_min_f32_e32 v9, 0x40e00000, v9
	v_mul_f32_e32 v10, 0xc01d265f, v9
	v_exp_f32_e32 v10, v10
	v_fmamk_f32 v4, v138, 0x3d000000, v74
	v_med3_f32 v4, v4, s69, v247
	v_add_f32_e32 v10, 1.0, v10
	v_rcp_f32_e32 v10, v10
	v_fma_f32 v5, v5, v4, v5
	v_fmamk_f32 v4, v139, 0x3d000000, v75
	v_med3_f32 v4, v4, s69, v247
	v_mul_f32_e32 v9, v9, v10
	v_add_f32_e32 v10, 1.0, v12
	v_rcp_f32_e32 v10, v10
	v_fma_f32 v6, v6, v4, v6
	v_fmamk_f32 v4, v140, 0x3d000000, v76
	v_med3_f32 v4, v4, s69, v247
	v_mul_f32_e32 v10, v11, v10
	v_fmamk_f32 v11, v136, 0x3d000000, v72
	v_min_f32_e32 v11, 0x40e00000, v11
	v_fma_f32 v7, v7, v4, v7
	v_fmamk_f32 v4, v141, 0x3d000000, v77
	v_mul_f32_e32 v12, 0xc01d265f, v11
	v_med3_f32 v4, v4, s69, v247
	v_exp_f32_e32 v12, v12
	v_fma_f32 v8, v8, v4, v8
	v_fmamk_f32 v4, v130, 0x3d000000, v78
	v_med3_f32 v4, v4, s69, v247
	v_fmamk_f32 v13, v137, 0x3d000000, v73
	v_min_f32_e32 v13, 0x40e00000, v13
	v_fma_f32 v9, v9, v4, v9
	v_fmamk_f32 v4, v131, 0x3d000000, v79
	v_add_f32_e32 v12, 1.0, v12
	v_mul_f32_e32 v14, 0xc01d265f, v13
	v_med3_f32 v4, v4, s69, v247
	v_rcp_f32_e32 v12, v12
	v_exp_f32_e32 v14, v14
	v_fma_f32 v10, v10, v4, v10
	v_fmamk_f32 v4, v132, 0x3d000000, v80
	v_med3_f32 v4, v4, s69, v247
	v_mul_f32_e32 v11, v11, v12
	v_add_f32_e32 v12, 1.0, v14
	v_fma_f32 v11, v11, v4, v11
	v_fmamk_f32 v4, v133, 0x3d000000, v81
	v_rcp_f32_e32 v12, v12
	v_med3_f32 v14, v4, s69, v247
	v_cvt_pk_fp8_f32 v4, v5, v6
	v_cvt_pk_fp8_f32 v5, v9, v10
	v_mul_f32_e32 v12, v13, v12
	v_fma_f32 v6, v12, v14, v12
	v_cvt_pk_fp8_f32 v5, v11, v6 op_sel:[0,0,1]
	v_fmamk_f32 v6, v126, 0x3d000000, v66
	v_cvt_pk_fp8_f32 v4, v7, v8 op_sel:[0,0,1]
	v_min_f32_e32 v8, 0x40e00000, v6
	v_mul_f32_e32 v6, 0xc01d265f, v8
	v_exp_f32_e32 v9, v6
	v_add_co_u32_e32 v6, vcc, s70, v2
	v_fmamk_f32 v11, v119, 0x3d000000, v71
	s_nop 0
	v_addc_co_u32_e32 v7, vcc, 0, v3, vcc
	global_store_dwordx2 v[6:7], v[4:5], off
	v_fmamk_f32 v6, v127, 0x3d000000, v67
	v_min_f32_e32 v6, 0x40e00000, v6
	v_mul_f32_e32 v7, 0xc01d265f, v6
	v_exp_f32_e32 v7, v7
	v_add_f32_e32 v5, 1.0, v9
	v_rcp_f32_e32 v5, v5
	v_fmamk_f32 v9, v129, 0x3d000000, v69
	v_add_f32_e32 v7, 1.0, v7
	v_rcp_f32_e32 v7, v7
	v_mul_f32_e32 v5, v8, v5
	v_min_f32_e32 v9, 0x40e00000, v9
	v_mul_f32_e32 v10, 0xc01d265f, v9
	v_mul_f32_e32 v6, v6, v7
	v_fmamk_f32 v7, v128, 0x3d000000, v68
	v_min_f32_e32 v7, 0x40e00000, v7
	v_mul_f32_e32 v8, 0xc01d265f, v7
	v_exp_f32_e32 v8, v8
	v_exp_f32_e32 v10, v10
	v_min_f32_e32 v11, 0x40e00000, v11
	v_add_f32_e32 v8, 1.0, v8
	v_rcp_f32_e32 v8, v8
	v_mul_f32_e32 v12, 0xc01d265f, v11
	v_exp_f32_e32 v12, v12
	v_mul_f32_e32 v7, v7, v8
	v_add_f32_e32 v8, 1.0, v10
	v_rcp_f32_e32 v8, v8
	v_fmamk_f32 v4, v122, 0x3d000000, v74
	v_med3_f32 v4, v4, s69, v247
	v_mul_f32_e32 v8, v9, v8
	v_fmamk_f32 v9, v118, 0x3d000000, v70
	v_min_f32_e32 v9, 0x40e00000, v9
	v_mul_f32_e32 v10, 0xc01d265f, v9
	v_exp_f32_e32 v10, v10
	v_fma_f32 v5, v5, v4, v5
	v_fmamk_f32 v4, v123, 0x3d000000, v75
	v_med3_f32 v4, v4, s69, v247
	v_add_f32_e32 v10, 1.0, v10
	v_rcp_f32_e32 v10, v10
	v_fma_f32 v6, v6, v4, v6
	v_fmamk_f32 v4, v124, 0x3d000000, v76
	v_mul_f32_e32 v9, v9, v10
	v_add_f32_e32 v10, 1.0, v12
	v_rcp_f32_e32 v10, v10
	v_med3_f32 v4, v4, s69, v247
	v_fma_f32 v7, v7, v4, v7
	v_mul_f32_e32 v10, v11, v10
	v_fmamk_f32 v11, v120, 0x3d000000, v72
	v_min_f32_e32 v11, 0x40e00000, v11
	v_fmamk_f32 v4, v125, 0x3d000000, v77
	v_mul_f32_e32 v12, 0xc01d265f, v11
	v_med3_f32 v4, v4, s69, v247
	v_exp_f32_e32 v12, v12
	v_fma_f32 v8, v8, v4, v8
	v_fmamk_f32 v4, v114, 0x3d000000, v78
	v_med3_f32 v4, v4, s69, v247
	v_fmamk_f32 v13, v121, 0x3d000000, v73
	v_min_f32_e32 v13, 0x40e00000, v13
	v_fma_f32 v9, v9, v4, v9
	v_fmamk_f32 v4, v115, 0x3d000000, v79
	v_add_f32_e32 v12, 1.0, v12
	v_mul_f32_e32 v14, 0xc01d265f, v13
	v_med3_f32 v4, v4, s69, v247
	v_rcp_f32_e32 v12, v12
	v_exp_f32_e32 v14, v14
	v_fma_f32 v10, v10, v4, v10
	v_fmamk_f32 v4, v116, 0x3d000000, v80
	v_med3_f32 v4, v4, s69, v247
	v_mul_f32_e32 v11, v11, v12
	v_add_f32_e32 v12, 1.0, v14
	v_fma_f32 v11, v11, v4, v11
	v_fmamk_f32 v4, v117, 0x3d000000, v81
	v_rcp_f32_e32 v12, v12
	v_med3_f32 v14, v4, s69, v247
	v_cvt_pk_fp8_f32 v4, v5, v6
	v_cvt_pk_fp8_f32 v5, v9, v10
	v_mul_f32_e32 v12, v13, v12
	v_fma_f32 v6, v12, v14, v12
	v_cvt_pk_fp8_f32 v5, v11, v6 op_sel:[0,0,1]
	v_fmamk_f32 v6, v110, 0x3d000000, v66
	v_cvt_pk_fp8_f32 v4, v7, v8 op_sel:[0,0,1]
	v_min_f32_e32 v8, 0x40e00000, v6
	v_mul_f32_e32 v6, 0xc01d265f, v8
	v_exp_f32_e32 v9, v6
	v_add_co_u32_e32 v6, vcc, s71, v2
	v_fmamk_f32 v11, v103, 0x3d000000, v71
	s_nop 0
	v_addc_co_u32_e32 v7, vcc, 0, v3, vcc
	global_store_dwordx2 v[6:7], v[4:5], off
	v_fmamk_f32 v6, v111, 0x3d000000, v67
	v_min_f32_e32 v6, 0x40e00000, v6
	v_mul_f32_e32 v7, 0xc01d265f, v6
	v_exp_f32_e32 v7, v7
	v_add_f32_e32 v5, 1.0, v9
	v_rcp_f32_e32 v5, v5
	v_fmamk_f32 v9, v113, 0x3d000000, v69
	v_add_f32_e32 v7, 1.0, v7
	v_rcp_f32_e32 v7, v7
	v_mul_f32_e32 v5, v8, v5
	v_min_f32_e32 v9, 0x40e00000, v9
	v_mul_f32_e32 v10, 0xc01d265f, v9
	v_mul_f32_e32 v6, v6, v7
	v_fmamk_f32 v7, v112, 0x3d000000, v68
	v_min_f32_e32 v7, 0x40e00000, v7
	v_mul_f32_e32 v8, 0xc01d265f, v7
	v_exp_f32_e32 v8, v8
	v_exp_f32_e32 v10, v10
	v_min_f32_e32 v11, 0x40e00000, v11
	v_add_f32_e32 v8, 1.0, v8
	v_rcp_f32_e32 v8, v8
	v_mul_f32_e32 v12, 0xc01d265f, v11
	v_exp_f32_e32 v12, v12
	v_mul_f32_e32 v7, v7, v8
	v_add_f32_e32 v8, 1.0, v10
	v_rcp_f32_e32 v8, v8
	v_fmamk_f32 v4, v106, 0x3d000000, v74
	v_med3_f32 v4, v4, s69, v247
	v_mul_f32_e32 v8, v9, v8
	v_fmamk_f32 v9, v102, 0x3d000000, v70
	v_min_f32_e32 v9, 0x40e00000, v9
	v_mul_f32_e32 v10, 0xc01d265f, v9
	v_exp_f32_e32 v10, v10
	v_fma_f32 v5, v5, v4, v5
	v_fmamk_f32 v4, v107, 0x3d000000, v75
	v_med3_f32 v4, v4, s69, v247
	v_add_f32_e32 v10, 1.0, v10
	v_rcp_f32_e32 v10, v10
	v_fma_f32 v6, v6, v4, v6
	v_fmamk_f32 v4, v108, 0x3d000000, v76
	v_mul_f32_e32 v9, v9, v10
	v_add_f32_e32 v10, 1.0, v12
	v_rcp_f32_e32 v10, v10
	v_med3_f32 v4, v4, s69, v247
	v_fma_f32 v7, v7, v4, v7
	v_mul_f32_e32 v10, v11, v10
	v_fmamk_f32 v11, v104, 0x3d000000, v72
	v_min_f32_e32 v11, 0x40e00000, v11
	v_fmamk_f32 v4, v109, 0x3d000000, v77
	v_mul_f32_e32 v12, 0xc01d265f, v11
	v_med3_f32 v4, v4, s69, v247
	v_exp_f32_e32 v12, v12
	v_fma_f32 v8, v8, v4, v8
	v_fmamk_f32 v4, v98, 0x3d000000, v78
	v_med3_f32 v4, v4, s69, v247
	v_fmamk_f32 v13, v105, 0x3d000000, v73
	v_min_f32_e32 v13, 0x40e00000, v13
	v_fma_f32 v9, v9, v4, v9
	v_fmamk_f32 v4, v99, 0x3d000000, v79
	v_add_f32_e32 v12, 1.0, v12
	v_mul_f32_e32 v14, 0xc01d265f, v13
	v_med3_f32 v4, v4, s69, v247
	v_rcp_f32_e32 v12, v12
	v_exp_f32_e32 v14, v14
	v_fma_f32 v10, v10, v4, v10
	v_fmamk_f32 v4, v100, 0x3d000000, v80
	v_med3_f32 v4, v4, s69, v247
	v_mul_f32_e32 v11, v11, v12
	v_add_f32_e32 v12, 1.0, v14
	v_fma_f32 v11, v11, v4, v11
	v_fmamk_f32 v4, v101, 0x3d000000, v81
	v_rcp_f32_e32 v12, v12
	v_med3_f32 v14, v4, s69, v247
	v_cvt_pk_fp8_f32 v4, v5, v6
	v_cvt_pk_fp8_f32 v5, v9, v10
	v_mul_f32_e32 v12, v13, v12
	v_fma_f32 v6, v12, v14, v12
	v_cvt_pk_fp8_f32 v5, v11, v6 op_sel:[0,0,1]
	v_fmamk_f32 v6, v94, 0x3d000000, v66
	v_cvt_pk_fp8_f32 v4, v7, v8 op_sel:[0,0,1]
	v_min_f32_e32 v8, 0x40e00000, v6
	v_mul_f32_e32 v6, 0xc01d265f, v8
	v_exp_f32_e32 v9, v6
	v_add_co_u32_e32 v6, vcc, s72, v2
	v_fmamk_f32 v11, v87, 0x3d000000, v71
	s_nop 0
	v_addc_co_u32_e32 v7, vcc, 0, v3, vcc
	global_store_dwordx2 v[6:7], v[4:5], off
	v_fmamk_f32 v6, v95, 0x3d000000, v67
	v_min_f32_e32 v6, 0x40e00000, v6
	v_mul_f32_e32 v7, 0xc01d265f, v6
	v_exp_f32_e32 v7, v7
	v_add_f32_e32 v5, 1.0, v9
	v_rcp_f32_e32 v5, v5
	v_fmamk_f32 v9, v97, 0x3d000000, v69
	v_add_f32_e32 v7, 1.0, v7
	v_rcp_f32_e32 v7, v7
	v_mul_f32_e32 v5, v8, v5
	v_min_f32_e32 v9, 0x40e00000, v9
	v_mul_f32_e32 v10, 0xc01d265f, v9
	v_mul_f32_e32 v6, v6, v7
	v_fmamk_f32 v7, v96, 0x3d000000, v68
	v_min_f32_e32 v7, 0x40e00000, v7
	v_mul_f32_e32 v8, 0xc01d265f, v7
	v_exp_f32_e32 v8, v8
	v_exp_f32_e32 v10, v10
	v_min_f32_e32 v11, 0x40e00000, v11
	v_add_f32_e32 v8, 1.0, v8
	v_rcp_f32_e32 v8, v8
	v_mul_f32_e32 v12, 0xc01d265f, v11
	v_exp_f32_e32 v12, v12
	v_mul_f32_e32 v7, v7, v8
	v_add_f32_e32 v8, 1.0, v10
	v_rcp_f32_e32 v8, v8
	v_fmamk_f32 v4, v90, 0x3d000000, v74
	v_med3_f32 v4, v4, s69, v247
	v_mul_f32_e32 v8, v9, v8
	v_fmamk_f32 v9, v86, 0x3d000000, v70
	v_min_f32_e32 v9, 0x40e00000, v9
	v_mul_f32_e32 v10, 0xc01d265f, v9
	v_exp_f32_e32 v10, v10
	v_fma_f32 v5, v5, v4, v5
	v_fmamk_f32 v4, v91, 0x3d000000, v75
	v_med3_f32 v4, v4, s69, v247
	v_add_f32_e32 v10, 1.0, v10
	v_rcp_f32_e32 v10, v10
	v_fma_f32 v6, v6, v4, v6
	v_fmamk_f32 v4, v92, 0x3d000000, v76
	v_mul_f32_e32 v9, v9, v10
	v_add_f32_e32 v10, 1.0, v12
	v_rcp_f32_e32 v10, v10
	v_med3_f32 v4, v4, s69, v247
	v_fma_f32 v7, v7, v4, v7
	v_mul_f32_e32 v10, v11, v10
	v_fmamk_f32 v11, v88, 0x3d000000, v72
	v_min_f32_e32 v11, 0x40e00000, v11
	v_fmamk_f32 v4, v93, 0x3d000000, v77
	v_mul_f32_e32 v12, 0xc01d265f, v11
	v_med3_f32 v4, v4, s69, v247
	v_exp_f32_e32 v12, v12
	v_fma_f32 v8, v8, v4, v8
	v_fmamk_f32 v4, v82, 0x3d000000, v78
	v_med3_f32 v4, v4, s69, v247
	v_fmamk_f32 v13, v89, 0x3d000000, v73
	v_min_f32_e32 v13, 0x40e00000, v13
	v_fma_f32 v9, v9, v4, v9
	v_fmamk_f32 v4, v83, 0x3d000000, v79
	v_add_f32_e32 v12, 1.0, v12
	v_mul_f32_e32 v14, 0xc01d265f, v13
	v_med3_f32 v4, v4, s69, v247
	v_rcp_f32_e32 v12, v12
	v_exp_f32_e32 v14, v14
	v_fma_f32 v10, v10, v4, v10
	v_fmamk_f32 v4, v84, 0x3d000000, v80
	v_med3_f32 v4, v4, s69, v247
	v_mul_f32_e32 v11, v11, v12
	v_add_f32_e32 v12, 1.0, v14
	v_fma_f32 v11, v11, v4, v11
	v_fmamk_f32 v4, v85, 0x3d000000, v81
	v_rcp_f32_e32 v12, v12
	v_med3_f32 v14, v4, s69, v247
	v_cvt_pk_fp8_f32 v4, v5, v6
	v_cvt_pk_fp8_f32 v5, v9, v10
	v_mul_f32_e32 v12, v13, v12
	v_fma_f32 v6, v12, v14, v12
	v_cvt_pk_fp8_f32 v4, v7, v8 op_sel:[0,0,1]
	v_cvt_pk_fp8_f32 v5, v11, v6 op_sel:[0,0,1]
	v_add_co_u32_e32 v2, vcc, 0x58000, v2
	s_nop 1
	v_addc_co_u32_e32 v3, vcc, 0, v3, vcc
	s_and_b64 vcc, exec, s[4:5]
	s_mov_b64 s[4:5], -1
	global_store_dwordx2 v[2:3], v[4:5], off
	s_cbranch_vccnz .LBB0_1569
	s_andn2_b64 vcc, exec, s[18:19]
	s_cbranch_vccnz .LBB0_1568
	s_barrier
	s_branch .LBB0_1568

.LBB0_1659:
	s_ashr_i32 s47, s46, 31
	s_lshl_b64 s[42:43], s[46:47], 19
	s_add_u32 s50, s1, s42
	s_addc_u32 s51, s3, s43
	s_and_b64 s[42:43], s[4:5], exec
	s_cselect_b32 s47, s51, s59
	s_cselect_b32 s81, s50, s58
	s_ashr_i32 s49, s48, 31
	s_lshl_b64 s[42:43], s[48:49], 19
	s_add_u32 s52, s14, s42
	s_addc_u32 s53, s15, s43
	s_and_b64 s[42:43], s[4:5], exec
	s_cselect_b32 s49, s53, s61
	s_cselect_b32 s82, s52, s60
	s_ashr_i32 s55, s54, 31
	s_lshl_b64 s[42:43], s[54:55], 13
	s_lshl_b32 s54, s2, 8
	s_lshl_b32 s83, s56, 8
	s_ashr_i32 s55, s54, 31
	s_add_i32 s83, s83, s69
	s_waitcnt lgkmcnt(0)
	s_add_u32 s2, s8, s42
	s_addc_u32 s35, s9, s43
	s_lshl_b64 s[42:43], s[54:55], 2
	s_add_u32 s2, s2, s42
	s_addc_u32 s35, s35, s43
	s_add_u32 s56, s2, s74
	s_addc_u32 s57, s35, 0
	s_add_u32 s58, s58, 0x40080
	s_addc_u32 s59, s59, 0
	s_add_u32 s55, s60, 0x100
	v_mov_b32_e32 v80, 0
	s_addc_u32 s84, s61, 0
	s_mov_b32 s85, -2
	v_mov_b64_e32 v[80:81], 0
	v_mov_b64_e32 v[82:83], 0
	v_mov_b64_e32 v[84:85], 0
	v_mov_b64_e32 v[86:87], 0
	v_mov_b64_e32 v[88:89], 0
	v_mov_b64_e32 v[90:91], 0
	v_mov_b64_e32 v[92:93], 0
	v_mov_b64_e32 v[94:95], 0
	v_mov_b64_e32 v[96:97], 0
	v_mov_b64_e32 v[98:99], 0
	v_mov_b64_e32 v[100:101], 0
	v_mov_b64_e32 v[102:103], 0
	v_mov_b64_e32 v[104:105], 0
	v_mov_b64_e32 v[106:107], 0
	v_mov_b64_e32 v[108:109], 0
	v_mov_b64_e32 v[110:111], 0
	v_mov_b64_e32 v[112:113], 0
	v_mov_b64_e32 v[114:115], 0
	v_mov_b64_e32 v[116:117], 0
	v_mov_b64_e32 v[118:119], 0
	v_mov_b64_e32 v[120:121], 0
	v_mov_b64_e32 v[122:123], 0
	v_mov_b64_e32 v[124:125], 0
	v_mov_b64_e32 v[126:127], 0
	v_mov_b64_e32 v[128:129], 0
	v_mov_b64_e32 v[130:131], 0
	v_mov_b64_e32 v[132:133], 0
	v_mov_b64_e32 v[134:135], 0
	v_mov_b64_e32 v[136:137], 0
	v_mov_b64_e32 v[138:139], 0
	v_mov_b64_e32 v[140:141], 0
	v_mov_b64_e32 v[142:143], 0
	v_mov_b64_e32 v[144:145], 0
	v_mov_b64_e32 v[146:147], 0
	v_mov_b64_e32 v[148:149], 0
	v_mov_b64_e32 v[150:151], 0
	v_mov_b64_e32 v[152:153], 0
	v_mov_b64_e32 v[154:155], 0
	v_mov_b64_e32 v[156:157], 0
	v_mov_b64_e32 v[158:159], 0
	v_mov_b64_e32 v[160:161], 0
	v_mov_b64_e32 v[162:163], 0
	v_mov_b64_e32 v[164:165], 0
	v_mov_b64_e32 v[166:167], 0
	v_mov_b64_e32 v[168:169], 0
	v_mov_b64_e32 v[170:171], 0
	v_mov_b64_e32 v[172:173], 0
	v_mov_b64_e32 v[174:175], 0
	v_mov_b64_e32 v[176:177], 0
	v_mov_b64_e32 v[178:179], 0
	v_mov_b64_e32 v[180:181], 0
	v_mov_b64_e32 v[182:183], 0
	v_mov_b64_e32 v[184:185], 0
	v_mov_b64_e32 v[186:187], 0
	v_mov_b64_e32 v[188:189], 0
	v_mov_b64_e32 v[190:191], 0
	v_mov_b64_e32 v[192:193], 0
	v_mov_b64_e32 v[194:195], 0
	v_mov_b64_e32 v[196:197], 0
	v_mov_b64_e32 v[198:199], 0
	v_mov_b64_e32 v[200:201], 0
	v_mov_b64_e32 v[202:203], 0
	v_mov_b64_e32 v[204:205], 0
	v_mov_b64_e32 v[206:207], 0
	s_branch .LBB0_1661
